# moved layer-0 gate/up/down weight conversion out of the prologue into the idle workgroups of layer-0 merge phase (hand-written convert routine)
# speedup vs baseline: 1.0271x; 1.0124x over previous
; __device__ __forceinline__ void ph_prologue(LAS unsigned char* lds) { PH_PRE
;     ...
;     convert_weights(a, 0, lds, CV_SQ_END, CV_END, gw, NGW, wave, lane);
.LBB0_180:
	s_branch .LBB0_363
	s_cbranch_scc1 .LBB0_363
	s_add_i32 s35, s37, 0x25b0
	s_cmpk_gt_u32 s35, 0x30af
	s_cbranch_scc0 .LBB0_185
	s_cmpk_gt_u32 s35, 0x3baf
	s_cbranch_scc1 .LBB0_183
	s_getpc_b64 s[98:99]

; #define LAS __attribute__((address_space(3)))
; __device__ __forceinline__ TrP tr_decode(ArgsP a, int l, int it) {
;     unsigned char* ws = a->ws;
;     constexpr int I_IN = 16 * 355, I_Q = 4 * 96, I_KV = 4 * 128, I_SQ = 16 * 64, I_G = 16 * 176;
;     TrP p; p.gk = nullptr; int r = it;
;     ...
;     if (r < I_IN) { const int kb = r / 355, nb = r % 355; TRSET(a->in[8] + (size_t)l * DM * NIN_SRC, NIN_SRC, (bf16_t*)(ws + WS_WIN), DM, 0, win_drow(32 * nb), kb, 32 * nb); return p; } r -= I_IN;
;     if (r < I_Q) { const int kb = r / 96, nb = r % 96; TRSET(a->in[15] + (size_t)l * 512 * 3072, 3072, (bf16_t*)(ws + WS_WQ), 512, 0, 32 * nb, kb, 32 * nb); p.gk = a->in[14] + l * 512; return p; } r -= I_Q;
;     if (r < I_KV) { const int kb = r / 128, nb = r % 128; TRSET(a->in[17] + (size_t)l * 512 * 4096, 4096, (bf16_t*)(ws + WS_WKV), 512, 0, 32 * nb, kb, 32 * nb); p.gk = a->in[16] + l * 512; return p; } r -= I_KV;
;     if (r < I_SQ) { const int kb = r / 64, nb = r % 64; TRSET(a->in[18] + (size_t)l * DM * DM, DM, (bf16_t*)(ws + WS_WAB), 4096, 0, 32 * nb, kb, 32 * nb); return p; } r -= I_SQ;
;     if (r < I_SQ) { const int kb = r / 64, nb = r % 64; TRSET(a->in[19] + (size_t)l * DM * DM, DM, (bf16_t*)(ws + WS_WAB), 4096, 2048, 32 * nb, kb, 32 * nb); return p; } r -= I_SQ;
;     if (r < I_SQ) { const int kb = r / 64, nb = r % 64; TRSET(a->in[20] + (size_t)l * DM * DM, DM, (bf16_t*)(ws + WS_WO), DM, 0, 32 * nb, kb, 32 * nb); return p; } r -= I_SQ;
;     if (r < I_G) { const int kb = r / 176, nb = r % 176, n0 = 32 * nb; TRSET(a->in[21] + (size_t)l * DM * DFF, DFF, (bf16_t*)(ws + WS_WGU), DM, 0, (n0 >> 7) * 256 + (n0 & 127), kb, n0); return p; } r -= I_G;
; __device__ __forceinline__ void convert_weights(ArgsP a, int l, LAS unsigned char* lds, int lo, int hi, int widx, int nw, int wave, int lane) {
;     LAS float* scr = (LAS float*)(lds + wave * 17408);
;     f32x4 v[16];
;     int it = lo + widx; if (widx < 0 || it >= hi) return;
;     TrP p = tr_decode(a, l, it);
;     ...
;     TR_LOAD(p);
;     for (;;) {
; #pragma unroll
;         for (int i = 0; i < 16; ++i) { LAS float* d = scr + (8 * i + (lane >> 3)) * 33 + 4 * (lane & 7); d[0] = v[i][0]; d[1] = v[i][1]; d[2] = v[i][2]; d[3] = v[i][3]; }
;         const int itn = it + nw; const bool more = itn < hi; TrP pn = p;
;         if (more) { pn = tr_decode(a, l, itn); TR_LOAD(pn); }
.LBB0_1917:
	s_mov_b64 s[82:83], 0x25800000
	s_and_b64 vcc, exec, s[66:67]
	s_cbranch_vccz .Lmy_cvm_done
	s_cmp_lt_u32 s8, 32
	s_cbranch_scc1 .Lmy_cvm_done
	v_and_b32_e32 v0, 63, v206
	v_lshrrev_b32_e32 v1, 6, v206
	s_load_dwordx2 s[14:15], s[0:1], 0xa8
	s_load_dwordx2 s[16:17], s[0:1], 0xb0
	s_load_dwordx2 s[18:19], s[0:1], 0xb8
	s_load_dwordx2 s[20:21], s[0:1], 0xd0
	v_readfirstlane_b32 s2, v1
	v_lshrrev_b32_e32 v2, 3, v0
	v_and_b32_e32 v3, 7, v0
	v_lshrrev_b32_e32 v5, 4, v0
	v_and_b32_e32 v6, 15, v0
	s_nop 3
	s_sub_i32 s3, s8, 32
	s_lshl_b32 s3, s3, 3
	s_add_i32 s3, s3, s2
	s_mul_i32 s4, s2, 0x4400
	v_mul_u32_u24_e32 v4, 0x84, v2
	v_lshl_add_u32 v4, v3, 4, v4
	v_add_u32_e32 v4, s4, v4
	v_mul_u32_u24_e32 v7, 0x420, v5
	v_lshl_add_u32 v7, v6, 2, v7
	v_add_u32_e32 v7, s4, v7
	v_mul_u32_u24_e32 v8, 0x5800, v2
	v_lshl_add_u32 v8, v3, 4, v8
	v_lshlrev_b32_e32 v9, 13, v2
	v_lshl_add_u32 v9, v3, 4, v9
	v_lshlrev_b32_e32 v10, 12, v6
	v_lshl_add_u32 v10, v5, 4, v10
	v_add_u32_e32 v12, 0x10000, v10
	v_mul_u32_u24_e32 v11, 0x2c00, v6
	v_lshl_add_u32 v11, v5, 4, v11
	v_add_u32_e32 v13, 0x2c000, v11
	s_waitcnt lgkmcnt(0)
	s_add_u32 s22, s20, 0x5400000
	s_addc_u32 s23, s21, 0
	s_add_u32 s24, s20, 0x8000000
	s_addc_u32 s25, s21, 0
	s_cmp_ge_u32 s3, 8448
	s_cbranch_scc1 .Lmy_cvm_exit
	s_cmp_ge_u32 s3, 0x1600
	s_cbranch_scc1 .Lmy_cvm_dn0
	s_cmp_ge_u32 s3, 0xb00
	s_cselect_b32 s40, 0xb00, 0
	s_cselect_b32 s48, 128, 0
	s_cselect_b32 s26, s16, s14
	s_cselect_b32 s27, s17, s15
	s_sub_i32 s40, s3, s40
	s_mul_i32 s51, s40, 0xba2f
	s_lshr_b32 s51, s51, 23
	s_mul_i32 s54, s51, 0xb0
	s_sub_i32 s54, s40, s54
	s_mul_hi_u32 s55, s51, 0x2c0000
	s_mul_i32 s57, s51, 0x2c0000
	s_add_u32 s26, s26, s57
	s_addc_u32 s27, s27, s55
	s_lshl_b32 s57, s54, 7
	s_add_u32 s26, s26, s57
	s_addc_u32 s27, s27, 0
	s_lshr_b32 s57, s54, 2
	s_lshl_b32 s57, s57, 8
	s_and_b32 s58, s54, 3
	s_lshl_b32 s58, s58, 5
	s_add_i32 s57, s57, s58
	s_add_i32 s57, s57, s48
	s_lshl_b32 s57, s57, 12
	s_lshl_b32 s58, s51, 8
	s_add_i32 s57, s57, s58
	s_add_u32 s68, s22, s57
	s_addc_u32 s69, s23, 0
	s_mov_b32 s31, 0x2c000
	s_mov_b32 s59, 0
	v_mov_b32_e32 v1, v8
	s_branch .Lmy_cvm_ld0
.Lmy_cvm_dn0:
	s_sub_i32 s40, s3, 0x1600
	s_lshr_b32 s51, s40, 6
	s_and_b32 s54, s40, 63
	s_lshl_b32 s57, s51, 20
	s_lshr_b32 s55, s51, 12
	s_add_u32 s26, s18, s57
	s_addc_u32 s27, s19, s55
	s_lshl_b32 s57, s54, 7
	s_add_u32 s26, s26, s57
	s_addc_u32 s27, s27, 0
	s_mul_i32 s57, s54, 0x58000
	s_lshl_b32 s58, s51, 8
	s_add_i32 s57, s57, s58
	s_add_u32 s68, s24, s57
	s_addc_u32 s69, s25, 0
	s_mov_b32 s31, 0x10000
	s_mov_b32 s59, 1
	v_mov_b32_e32 v1, v9
.Lmy_cvm_ld0:
	global_load_dwordx4 v[14:17], v1, s[26:27] nt
	s_add_u32 s26, s26, s31
	s_addc_u32 s27, s27, 0
	global_load_dwordx4 v[18:21], v1, s[26:27] nt
	s_add_u32 s26, s26, s31
	s_addc_u32 s27, s27, 0
	global_load_dwordx4 v[22:25], v1, s[26:27] nt
	s_add_u32 s26, s26, s31
	s_addc_u32 s27, s27, 0
	global_load_dwordx4 v[26:29], v1, s[26:27] nt
	s_add_u32 s26, s26, s31
	s_addc_u32 s27, s27, 0
	global_load_dwordx4 v[30:33], v1, s[26:27] nt
	s_add_u32 s26, s26, s31
	s_addc_u32 s27, s27, 0
	global_load_dwordx4 v[34:37], v1, s[26:27] nt
	s_add_u32 s26, s26, s31
	s_addc_u32 s27, s27, 0
	global_load_dwordx4 v[38:41], v1, s[26:27] nt
	s_add_u32 s26, s26, s31
	s_addc_u32 s27, s27, 0
	global_load_dwordx4 v[42:45], v1, s[26:27] nt
	s_add_u32 s26, s26, s31
	s_addc_u32 s27, s27, 0
	global_load_dwordx4 v[46:49], v1, s[26:27] nt
	s_add_u32 s26, s26, s31
	s_addc_u32 s27, s27, 0
	global_load_dwordx4 v[50:53], v1, s[26:27] nt
	s_add_u32 s26, s26, s31
	s_addc_u32 s27, s27, 0
	global_load_dwordx4 v[54:57], v1, s[26:27] nt
	s_add_u32 s26, s26, s31
	s_addc_u32 s27, s27, 0
	global_load_dwordx4 v[58:61], v1, s[26:27] nt
	s_add_u32 s26, s26, s31
	s_addc_u32 s27, s27, 0
	global_load_dwordx4 v[62:65], v1, s[26:27] nt
	s_add_u32 s26, s26, s31
	s_addc_u32 s27, s27, 0
	global_load_dwordx4 v[66:69], v1, s[26:27] nt
	s_add_u32 s26, s26, s31
	s_addc_u32 s27, s27, 0
	global_load_dwordx4 v[70:73], v1, s[26:27] nt
	s_add_u32 s26, s26, s31
	s_addc_u32 s27, s27, 0
	global_load_dwordx4 v[74:77], v1, s[26:27] nt
	s_waitcnt vmcnt(15)
	ds_write_b32 v4, v14 offset:0
	ds_write_b32 v4, v15 offset:4
	ds_write_b32 v4, v16 offset:8
	ds_write_b32 v4, v17 offset:12
	s_waitcnt vmcnt(14)
	ds_write_b32 v4, v18 offset:1056
	ds_write_b32 v4, v19 offset:1060
	ds_write_b32 v4, v20 offset:1064
	ds_write_b32 v4, v21 offset:1068
	s_waitcnt vmcnt(13)
	ds_write_b32 v4, v22 offset:2112
	ds_write_b32 v4, v23 offset:2116
	ds_write_b32 v4, v24 offset:2120
	ds_write_b32 v4, v25 offset:2124
	s_waitcnt vmcnt(12)
	ds_write_b32 v4, v26 offset:3168
	ds_write_b32 v4, v27 offset:3172
	ds_write_b32 v4, v28 offset:3176
	ds_write_b32 v4, v29 offset:3180
	s_waitcnt vmcnt(11)
	ds_write_b32 v4, v30 offset:4224
	ds_write_b32 v4, v31 offset:4228
	ds_write_b32 v4, v32 offset:4232
	ds_write_b32 v4, v33 offset:4236
	s_waitcnt vmcnt(10)
	ds_write_b32 v4, v34 offset:5280
	ds_write_b32 v4, v35 offset:5284
	ds_write_b32 v4, v36 offset:5288
	ds_write_b32 v4, v37 offset:5292
	s_waitcnt vmcnt(9)
	ds_write_b32 v4, v38 offset:6336
	ds_write_b32 v4, v39 offset:6340
	ds_write_b32 v4, v40 offset:6344
	ds_write_b32 v4, v41 offset:6348
	s_waitcnt vmcnt(8)
	ds_write_b32 v4, v42 offset:7392
	ds_write_b32 v4, v43 offset:7396
	ds_write_b32 v4, v44 offset:7400
	ds_write_b32 v4, v45 offset:7404
	s_waitcnt vmcnt(7)
	ds_write_b32 v4, v46 offset:8448
	ds_write_b32 v4, v47 offset:8452
	ds_write_b32 v4, v48 offset:8456
	ds_write_b32 v4, v49 offset:8460
	s_waitcnt vmcnt(6)
	ds_write_b32 v4, v50 offset:9504
	ds_write_b32 v4, v51 offset:9508
	ds_write_b32 v4, v52 offset:9512
	ds_write_b32 v4, v53 offset:9516
	s_waitcnt vmcnt(5)
	ds_write_b32 v4, v54 offset:10560
	ds_write_b32 v4, v55 offset:10564
	ds_write_b32 v4, v56 offset:10568
	ds_write_b32 v4, v57 offset:10572
	s_waitcnt vmcnt(4)
	ds_write_b32 v4, v58 offset:11616
	ds_write_b32 v4, v59 offset:11620
	ds_write_b32 v4, v60 offset:11624
	ds_write_b32 v4, v61 offset:11628
	s_waitcnt vmcnt(3)
	ds_write_b32 v4, v62 offset:12672
	ds_write_b32 v4, v63 offset:12676
	ds_write_b32 v4, v64 offset:12680
	ds_write_b32 v4, v65 offset:12684
	s_waitcnt vmcnt(2)
	ds_write_b32 v4, v66 offset:13728
	ds_write_b32 v4, v67 offset:13732
	ds_write_b32 v4, v68 offset:13736
	ds_write_b32 v4, v69 offset:13740
	s_waitcnt vmcnt(1)
	ds_write_b32 v4, v70 offset:14784
	ds_write_b32 v4, v71 offset:14788
	ds_write_b32 v4, v72 offset:14792
	ds_write_b32 v4, v73 offset:14796
	s_waitcnt vmcnt(0)
	ds_write_b32 v4, v74 offset:15840
	ds_write_b32 v4, v75 offset:15844
	ds_write_b32 v4, v76 offset:15848
	ds_write_b32 v4, v77 offset:15852
	s_branch .Lmy_cvm_mid
; #define LAS __attribute__((address_space(3)))
; __device__ __forceinline__ unsigned cvt_pk_bf16(float lo, float hi) { unsigned r; asm volatile("v_cvt_pk_bf16_f32 %0, %1, %2" : "=v"(r) : "v"(lo), "v"(hi)); return r; }
; #define TR_LOAD(P_) do { const float* s_ = (P_).src + (size_t)(lane >> 3) * (P_).N + 4 * (lane & 7); _Pragma("unroll") for (int i = 0; i < 16; ++i) v[i] = __builtin_nontemporal_load((const f32x4*)(s_ + (size_t)(8 * i) * (P_).N)); } while (0)
; __device__ __forceinline__ void convert_weights(ArgsP a, int l, LAS unsigned char* lds, int lo, int hi, int widx, int nw, int wave, int lane) {
;     ...
;     for (;;) {
; #pragma unroll
;         for (int i = 0; i < 16; ++i) { LAS float* d = scr + (8 * i + (lane >> 3)) * 33 + 4 * (lane & 7); d[0] = v[i][0]; d[1] = v[i][1]; d[2] = v[i][2]; d[3] = v[i][3]; }
;         const int itn = it + nw; const bool more = itn < hi; TrP pn = p;
;         if (more) { pn = tr_decode(a, l, itn); TR_LOAD(pn); }
;         asm volatile("s_waitcnt lgkmcnt(0)" ::: "memory");
; #pragma unroll
;         for (int j = 0; j < 8; ++j) { const int n = (lane & 15) + 16 * (j & 1), ch = (lane >> 4) + 4 * (j >> 1); const LAS float* sp = scr + (8 * ch) * 33 + n;
;             float gs[8];
; #pragma unroll
;             for (int e = 0; e < 8; ++e) gs[e] = p.gk ? p.gk[p.k0 + 8 * ch + e] : 1.f;
;             u32x4 o; o.x = cvt_pk_bf16(sp[0 * 33] * gs[0], sp[1 * 33] * gs[1]); o.y = cvt_pk_bf16(sp[2 * 33] * gs[2], sp[3 * 33] * gs[3]); o.z = cvt_pk_bf16(sp[4 * 33] * gs[4], sp[5 * 33] * gs[5]); o.w = cvt_pk_bf16(sp[6 * 33] * gs[6], sp[7 * 33] * gs[7]);
;             *(u32x4*)(p.dst + (size_t)n * p.ldd + 8 * ch) = o; }
.Lmy_cvm_loop:
	s_waitcnt vmcnt(23)
	ds_write_b32 v4, v14 offset:0
	ds_write_b32 v4, v15 offset:4
	ds_write_b32 v4, v16 offset:8
	ds_write_b32 v4, v17 offset:12
	s_waitcnt vmcnt(22)
	ds_write_b32 v4, v18 offset:1056
	ds_write_b32 v4, v19 offset:1060
	ds_write_b32 v4, v20 offset:1064
	ds_write_b32 v4, v21 offset:1068
	s_waitcnt vmcnt(21)
	ds_write_b32 v4, v22 offset:2112
	ds_write_b32 v4, v23 offset:2116
	ds_write_b32 v4, v24 offset:2120
	ds_write_b32 v4, v25 offset:2124
	s_waitcnt vmcnt(20)
	ds_write_b32 v4, v26 offset:3168
	ds_write_b32 v4, v27 offset:3172
	ds_write_b32 v4, v28 offset:3176
	ds_write_b32 v4, v29 offset:3180
	s_waitcnt vmcnt(19)
	ds_write_b32 v4, v30 offset:4224
	ds_write_b32 v4, v31 offset:4228
	ds_write_b32 v4, v32 offset:4232
	ds_write_b32 v4, v33 offset:4236
	s_waitcnt vmcnt(18)
	ds_write_b32 v4, v34 offset:5280
	ds_write_b32 v4, v35 offset:5284
	ds_write_b32 v4, v36 offset:5288
	ds_write_b32 v4, v37 offset:5292
	s_waitcnt vmcnt(17)
	ds_write_b32 v4, v38 offset:6336
	ds_write_b32 v4, v39 offset:6340
	ds_write_b32 v4, v40 offset:6344
	ds_write_b32 v4, v41 offset:6348
	s_waitcnt vmcnt(16)
	ds_write_b32 v4, v42 offset:7392
	ds_write_b32 v4, v43 offset:7396
	ds_write_b32 v4, v44 offset:7400
	ds_write_b32 v4, v45 offset:7404
	s_waitcnt vmcnt(15)
	ds_write_b32 v4, v46 offset:8448
	ds_write_b32 v4, v47 offset:8452
	ds_write_b32 v4, v48 offset:8456
	ds_write_b32 v4, v49 offset:8460
	s_waitcnt vmcnt(14)
	ds_write_b32 v4, v50 offset:9504
	ds_write_b32 v4, v51 offset:9508
	ds_write_b32 v4, v52 offset:9512
	ds_write_b32 v4, v53 offset:9516
	s_waitcnt vmcnt(13)
	ds_write_b32 v4, v54 offset:10560
	ds_write_b32 v4, v55 offset:10564
	ds_write_b32 v4, v56 offset:10568
	ds_write_b32 v4, v57 offset:10572
	s_waitcnt vmcnt(12)
	ds_write_b32 v4, v58 offset:11616
	ds_write_b32 v4, v59 offset:11620
	ds_write_b32 v4, v60 offset:11624
	ds_write_b32 v4, v61 offset:11628
	s_waitcnt vmcnt(11)
	ds_write_b32 v4, v62 offset:12672
	ds_write_b32 v4, v63 offset:12676
	ds_write_b32 v4, v64 offset:12680
	ds_write_b32 v4, v65 offset:12684
	s_waitcnt vmcnt(10)
	ds_write_b32 v4, v66 offset:13728
	ds_write_b32 v4, v67 offset:13732
	ds_write_b32 v4, v68 offset:13736
	ds_write_b32 v4, v69 offset:13740
	s_waitcnt vmcnt(9)
	ds_write_b32 v4, v70 offset:14784
	ds_write_b32 v4, v71 offset:14788
	ds_write_b32 v4, v72 offset:14792
	ds_write_b32 v4, v73 offset:14796
	s_waitcnt vmcnt(8)
	ds_write_b32 v4, v74 offset:15840
	ds_write_b32 v4, v75 offset:15844
	ds_write_b32 v4, v76 offset:15848
	ds_write_b32 v4, v77 offset:15852
.Lmy_cvm_mid:
	s_waitcnt lgkmcnt(0)
	s_mov_b64 s[42:43], s[68:69]
	s_cmp_eq_u32 s59, 0
	s_cselect_b64 vcc, -1, 0
	v_cndmask_b32_e32 v3, v11, v10, vcc
	v_cndmask_b32_e32 v5, v13, v12, vcc
	s_add_i32 s3, s3, 1792
	s_cmp_ge_u32 s3, 8448
	s_cbranch_scc1 .Lmy_cvm_rd
	s_cmp_ge_u32 s3, 0x1600
	s_cbranch_scc1 .Lmy_cvm_dn1
	s_cmp_ge_u32 s3, 0xb00
	s_cselect_b32 s40, 0xb00, 0
	s_cselect_b32 s48, 128, 0
	s_cselect_b32 s26, s16, s14
	s_cselect_b32 s27, s17, s15
	s_sub_i32 s40, s3, s40
	s_mul_i32 s51, s40, 0xba2f
	s_lshr_b32 s51, s51, 23
	s_mul_i32 s54, s51, 0xb0
	s_sub_i32 s54, s40, s54
	s_mul_hi_u32 s55, s51, 0x2c0000
	s_mul_i32 s57, s51, 0x2c0000
	s_add_u32 s26, s26, s57
	s_addc_u32 s27, s27, s55
	s_lshl_b32 s57, s54, 7
	s_add_u32 s26, s26, s57
	s_addc_u32 s27, s27, 0
	s_lshr_b32 s57, s54, 2
	s_lshl_b32 s57, s57, 8
	s_and_b32 s58, s54, 3
	s_lshl_b32 s58, s58, 5
	s_add_i32 s57, s57, s58
	s_add_i32 s57, s57, s48
	s_lshl_b32 s57, s57, 12
	s_lshl_b32 s58, s51, 8
	s_add_i32 s57, s57, s58
	s_add_u32 s68, s22, s57
	s_addc_u32 s69, s23, 0
	s_mov_b32 s31, 0x2c000
	s_mov_b32 s59, 0
	v_mov_b32_e32 v1, v8
	s_branch .Lmy_cvm_ld1

; #define LAS __attribute__((address_space(3)))
; __device__ __forceinline__ unsigned cvt_pk_bf16(float lo, float hi) { unsigned r; asm volatile("v_cvt_pk_bf16_f32 %0, %1, %2" : "=v"(r) : "v"(lo), "v"(hi)); return r; }
; #define TR_LOAD(P_) do { const float* s_ = (P_).src + (size_t)(lane >> 3) * (P_).N + 4 * (lane & 7); _Pragma("unroll") for (int i = 0; i < 16; ++i) v[i] = __builtin_nontemporal_load((const f32x4*)(s_ + (size_t)(8 * i) * (P_).N)); } while (0)
; __device__ __forceinline__ void convert_weights(ArgsP a, int l, LAS unsigned char* lds, int lo, int hi, int widx, int nw, int wave, int lane) {
;     ...
;     TR_LOAD(p);
;     for (;;) {
; #pragma unroll
;         for (int i = 0; i < 16; ++i) { LAS float* d = scr + (8 * i + (lane >> 3)) * 33 + 4 * (lane & 7); d[0] = v[i][0]; d[1] = v[i][1]; d[2] = v[i][2]; d[3] = v[i][3]; }
;         const int itn = it + nw; const bool more = itn < hi; TrP pn = p;
;         if (more) { pn = tr_decode(a, l, itn); TR_LOAD(pn); }
;         asm volatile("s_waitcnt lgkmcnt(0)" ::: "memory");
; #pragma unroll
;         for (int j = 0; j < 8; ++j) { const int n = (lane & 15) + 16 * (j & 1), ch = (lane >> 4) + 4 * (j >> 1); const LAS float* sp = scr + (8 * ch) * 33 + n;
;             float gs[8];
; #pragma unroll
;             for (int e = 0; e < 8; ++e) gs[e] = p.gk ? p.gk[p.k0 + 8 * ch + e] : 1.f;
;             u32x4 o; o.x = cvt_pk_bf16(sp[0 * 33] * gs[0], sp[1 * 33] * gs[1]); o.y = cvt_pk_bf16(sp[2 * 33] * gs[2], sp[3 * 33] * gs[3]); o.z = cvt_pk_bf16(sp[4 * 33] * gs[4], sp[5 * 33] * gs[5]); o.w = cvt_pk_bf16(sp[6 * 33] * gs[6], sp[7 * 33] * gs[7]);
;             *(u32x4*)(p.dst + (size_t)n * p.ldd + 8 * ch) = o; }
;         asm volatile("s_waitcnt lgkmcnt(0)" ::: "memory");
.Lmy_cvm_ld1:
	global_load_dwordx4 v[14:17], v1, s[26:27] nt
	s_add_u32 s26, s26, s31
	s_addc_u32 s27, s27, 0
	global_load_dwordx4 v[18:21], v1, s[26:27] nt
	s_add_u32 s26, s26, s31
	s_addc_u32 s27, s27, 0
	global_load_dwordx4 v[22:25], v1, s[26:27] nt
	s_add_u32 s26, s26, s31
	s_addc_u32 s27, s27, 0
	global_load_dwordx4 v[26:29], v1, s[26:27] nt
	s_add_u32 s26, s26, s31
	s_addc_u32 s27, s27, 0
	global_load_dwordx4 v[30:33], v1, s[26:27] nt
	s_add_u32 s26, s26, s31
	s_addc_u32 s27, s27, 0
	global_load_dwordx4 v[34:37], v1, s[26:27] nt
	s_add_u32 s26, s26, s31
	s_addc_u32 s27, s27, 0
	global_load_dwordx4 v[38:41], v1, s[26:27] nt
	s_add_u32 s26, s26, s31
	s_addc_u32 s27, s27, 0
	global_load_dwordx4 v[42:45], v1, s[26:27] nt
	s_add_u32 s26, s26, s31
	s_addc_u32 s27, s27, 0
	global_load_dwordx4 v[46:49], v1, s[26:27] nt
	s_add_u32 s26, s26, s31
	s_addc_u32 s27, s27, 0
	global_load_dwordx4 v[50:53], v1, s[26:27] nt
	s_add_u32 s26, s26, s31
	s_addc_u32 s27, s27, 0
	global_load_dwordx4 v[54:57], v1, s[26:27] nt
	s_add_u32 s26, s26, s31
	s_addc_u32 s27, s27, 0
	global_load_dwordx4 v[58:61], v1, s[26:27] nt
	s_add_u32 s26, s26, s31
	s_addc_u32 s27, s27, 0
	global_load_dwordx4 v[62:65], v1, s[26:27] nt
	s_add_u32 s26, s26, s31
	s_addc_u32 s27, s27, 0
	global_load_dwordx4 v[66:69], v1, s[26:27] nt
	s_add_u32 s26, s26, s31
	s_addc_u32 s27, s27, 0
	global_load_dwordx4 v[70:73], v1, s[26:27] nt
	s_add_u32 s26, s26, s31
	s_addc_u32 s27, s27, 0
	global_load_dwordx4 v[74:77], v1, s[26:27] nt
.Lmy_cvm_rd:
	ds_read_b32 v82, v7 offset:0
	ds_read_b32 v83, v7 offset:132
	ds_read_b32 v86, v7 offset:264
	ds_read_b32 v91, v7 offset:396
	ds_read_b32 v96, v7 offset:528
	ds_read_b32 v97, v7 offset:660
	ds_read_b32 v78, v7 offset:792
	ds_read_b32 v2, v7 offset:924
	s_waitcnt lgkmcnt(0)
	v_cvt_pk_bf16_f32 v92, v82, v83
	v_cvt_pk_bf16_f32 v93, v86, v91
	v_cvt_pk_bf16_f32 v94, v96, v97
	v_cvt_pk_bf16_f32 v95, v78, v2
	global_store_dwordx4 v3, v[92:95], s[42:43]
	ds_read_b32 v82, v7 offset:64
	ds_read_b32 v83, v7 offset:196
	ds_read_b32 v86, v7 offset:328
	ds_read_b32 v91, v7 offset:460
	ds_read_b32 v96, v7 offset:592
	ds_read_b32 v97, v7 offset:724
	ds_read_b32 v78, v7 offset:856
	ds_read_b32 v2, v7 offset:988
	s_waitcnt lgkmcnt(0)
	v_cvt_pk_bf16_f32 v92, v82, v83
	v_cvt_pk_bf16_f32 v93, v86, v91
	v_cvt_pk_bf16_f32 v94, v96, v97
	v_cvt_pk_bf16_f32 v95, v78, v2
	global_store_dwordx4 v5, v[92:95], s[42:43]
	ds_read_b32 v82, v7 offset:4224
	ds_read_b32 v83, v7 offset:4356
	ds_read_b32 v86, v7 offset:4488
	ds_read_b32 v91, v7 offset:4620
	ds_read_b32 v96, v7 offset:4752
	ds_read_b32 v97, v7 offset:4884
	ds_read_b32 v78, v7 offset:5016
	ds_read_b32 v2, v7 offset:5148
	s_waitcnt lgkmcnt(0)
	v_cvt_pk_bf16_f32 v92, v82, v83
	v_cvt_pk_bf16_f32 v93, v86, v91
	v_cvt_pk_bf16_f32 v94, v96, v97
	v_cvt_pk_bf16_f32 v95, v78, v2
	global_store_dwordx4 v3, v[92:95], s[42:43] offset:64
	ds_read_b32 v82, v7 offset:4288
	ds_read_b32 v83, v7 offset:4420
	ds_read_b32 v86, v7 offset:4552
	ds_read_b32 v91, v7 offset:4684
	ds_read_b32 v96, v7 offset:4816
	ds_read_b32 v97, v7 offset:4948
	ds_read_b32 v78, v7 offset:5080
	ds_read_b32 v2, v7 offset:5212
	s_waitcnt lgkmcnt(0)
	v_cvt_pk_bf16_f32 v92, v82, v83
	v_cvt_pk_bf16_f32 v93, v86, v91
	v_cvt_pk_bf16_f32 v94, v96, v97
	v_cvt_pk_bf16_f32 v95, v78, v2
	global_store_dwordx4 v5, v[92:95], s[42:43] offset:64
	ds_read_b32 v82, v7 offset:8448
	ds_read_b32 v83, v7 offset:8580
	ds_read_b32 v86, v7 offset:8712
	ds_read_b32 v91, v7 offset:8844
	ds_read_b32 v96, v7 offset:8976
	ds_read_b32 v97, v7 offset:9108
	ds_read_b32 v78, v7 offset:9240
	ds_read_b32 v2, v7 offset:9372
	s_waitcnt lgkmcnt(0)
	v_cvt_pk_bf16_f32 v92, v82, v83
	v_cvt_pk_bf16_f32 v93, v86, v91
	v_cvt_pk_bf16_f32 v94, v96, v97
	v_cvt_pk_bf16_f32 v95, v78, v2
	global_store_dwordx4 v3, v[92:95], s[42:43] offset:128
	ds_read_b32 v82, v7 offset:8512
	ds_read_b32 v83, v7 offset:8644
	ds_read_b32 v86, v7 offset:8776
	ds_read_b32 v91, v7 offset:8908
	ds_read_b32 v96, v7 offset:9040
	ds_read_b32 v97, v7 offset:9172
	ds_read_b32 v78, v7 offset:9304
	ds_read_b32 v2, v7 offset:9436
	s_waitcnt lgkmcnt(0)
	v_cvt_pk_bf16_f32 v92, v82, v83
	v_cvt_pk_bf16_f32 v93, v86, v91
	v_cvt_pk_bf16_f32 v94, v96, v97
	v_cvt_pk_bf16_f32 v95, v78, v2
	global_store_dwordx4 v5, v[92:95], s[42:43] offset:128
	ds_read_b32 v82, v7 offset:12672
	ds_read_b32 v83, v7 offset:12804
	ds_read_b32 v86, v7 offset:12936
	ds_read_b32 v91, v7 offset:13068
	ds_read_b32 v96, v7 offset:13200
	ds_read_b32 v97, v7 offset:13332
	ds_read_b32 v78, v7 offset:13464
	ds_read_b32 v2, v7 offset:13596
	s_waitcnt lgkmcnt(0)
	v_cvt_pk_bf16_f32 v92, v82, v83
	v_cvt_pk_bf16_f32 v93, v86, v91
	v_cvt_pk_bf16_f32 v94, v96, v97
	v_cvt_pk_bf16_f32 v95, v78, v2
	global_store_dwordx4 v3, v[92:95], s[42:43] offset:192
	ds_read_b32 v82, v7 offset:12736
	ds_read_b32 v83, v7 offset:12868
	ds_read_b32 v86, v7 offset:13000
	ds_read_b32 v91, v7 offset:13132
	ds_read_b32 v96, v7 offset:13264
	ds_read_b32 v97, v7 offset:13396
	ds_read_b32 v78, v7 offset:13528
	ds_read_b32 v2, v7 offset:13660
	s_waitcnt lgkmcnt(0)
	v_cvt_pk_bf16_f32 v92, v82, v83
	v_cvt_pk_bf16_f32 v93, v86, v91
	v_cvt_pk_bf16_f32 v94, v96, v97
	v_cvt_pk_bf16_f32 v95, v78, v2
	global_store_dwordx4 v5, v[92:95], s[42:43] offset:192
	s_cmp_lt_u32 s3, 8448
	s_cbranch_scc1 .Lmy_cvm_loop
; __device__ __forceinline__ void convert_weights(ArgsP a, int l, LAS unsigned char* lds, int lo, int hi, int widx, int nw, int wave, int lane) {
;     ...
;         if (!more) break;
;         p = pn; it = itn;
;     }
.Lmy_cvm_exit:
	s_waitcnt vmcnt(0) lgkmcnt(0)
.Lmy_cvm_done:
.LBB0_1918:
	s_mov_b64 s[4:5], s[0:1]
	s_load_dword s2, s[4:5], 0xd8
	s_add_i32 s31, s87, 7
	s_waitcnt lgkmcnt(0)
	s_cmp_gt_i32 s2, s56
	s_cbranch_scc1 .LBB0_1973
	s_load_dword s2, s[4:5], 0xdc
	s_waitcnt lgkmcnt(0)
	s_cmp_ge_i32 s31, s2
	s_cbranch_scc1 .LBB0_1973
	s_waitcnt vmcnt(0)
	s_waitcnt vmcnt(0)
	v_mov_b32_e32 v0, v206
	s_barrier
	s_nop 0
	v_cmp_eq_u32_e32 vcc, 0, v0
	s_and_saveexec_b64 s[2:3], vcc
	s_cbranch_execz .LBB0_1972
	v_readlane_b32 s7, v255, 0
	s_load_dwordx2 s[4:5], s[4:5], 0xd0
	s_getreg_b32 s6, hwreg(HW_REG_XCC_ID, 0, 4)
	v_mov_b32_e32 v0, s7
	s_waitcnt vmcnt(0) expcnt(0) lgkmcnt(0)
	ds_read_b32 v2, v0
	v_readlane_b32 s7, v255, 1
	s_and_b32 s10, s6, 15
	s_waitcnt lgkmcnt(0)
	v_cmp_ne_u32_e32 vcc, 0, v2
	v_mov_b32_e32 v0, s7
	ds_read_b32 v0, v0
	s_cbranch_vccnz .LBB0_1936
	s_add_u32 s6, s4, 0x4200
	s_addc_u32 s7, s5, 0
	s_add_u32 s12, s4, 0x4400
	s_addc_u32 s13, s5, 0
	s_add_u32 s14, s4, 0x4500
	s_addc_u32 s15, s5, 0
	s_add_u32 s16, s4, 0x4600
	s_addc_u32 s17, s5, 0
	s_add_u32 s18, s4, 0x4700
	s_addc_u32 s19, s5, 0
	s_add_u32 s20, s4, 0x4800
	s_addc_u32 s21, s5, 0
	s_add_u32 s22, s4, 0x4900
	s_addc_u32 s23, s5, 0
	s_add_u32 s24, s4, 0x4a00
	s_addc_u32 s25, s5, 0
	s_add_u32 s26, s4, 0x4b00
	s_addc_u32 s27, s5, 0
	s_add_u32 s68, s4, 0x4c00
	s_addc_u32 s69, s5, 0
	s_add_u32 s70, s4, 0x4d00
	s_addc_u32 s71, s5, 0
	s_add_u32 s72, s4, 0x4e00
	s_addc_u32 s73, s5, 0
	s_add_u32 s74, s4, 0x4f00
	s_addc_u32 s75, s5, 0
	s_add_u32 s76, s4, 0x5000
	s_addc_u32 s77, s5, 0
	s_add_u32 s78, s4, 0x5100
	s_addc_u32 s79, s5, 0
	s_add_u32 s80, s4, 0x5200
	s_addc_u32 s81, s5, 0
	s_add_u32 s82, s4, 0x5300
	s_addc_u32 s83, s5, 0
	s_mov_b32 s35, 1
	s_branch .LBB0_1924
